# scan-lds-trim-v5
# speedup vs baseline: 1.0212x; 1.0176x over previous
.LBB0_500:
	v_writelane_b32 v255, s80, 6
	v_writelane_b32 v255, s78, 4
	s_nop 1
	v_writelane_b32 v255, s79, 5
	v_writelane_b32 v255, s72, 7
	v_writelane_b32 v255, s97, 8
	s_or_b64 exec, exec, s[4:5]
	s_mov_b64 s[6:7], s[76:77]
	v_writelane_b32 v255, s71, 9
	s_cmpk_gt_i32 s71, 0xff
	s_barrier
	s_cbranch_scc1 .LBB0_614
	s_bfe_u32 s0, s70, 0x20006
	s_lshl_b32 s69, s0, 6
	s_cmpk_gt_u32 s70, 0xff
	v_or_b32_e32 v2, s69, v252
	s_cselect_b64 s[4:5], -1, 0
	v_lshlrev_b32_e32 v2, 7, v2
	s_or_b32 s73, s69, 0x100
	v_and_b32_e32 v141, 0x7c00, v2
	v_or_b32_e32 v2, s73, v252
	v_lshlrev_b32_e32 v2, 7, v2
	s_or_b32 s74, s69, 0x200
	v_and_b32_e32 v142, 0xfc00, v2
	v_or_b32_e32 v2, s74, v252
	s_movk_i32 s1, 0x20f
	v_mov_b32_e32 v3, 0xfffffdf0
	v_cmp_lt_u32_e32 vcc, s1, v2
	v_bfrev_b32_e32 v4, 64
	s_or_b32 s75, s69, 0x300
	v_cndmask_b32_e32 v3, 0, v3, vcc
	v_add_lshl_u32 v2, v3, v2, 7
	v_cndmask_b32_e32 v4, 0, v4, vcc
	v_and_b32_e32 v2, 0xfffffc00, v2
	v_add_u32_e32 v143, v2, v4
	v_or_b32_e32 v2, s75, v252
	v_mov_b32_e32 v3, 0x7ffef800
	v_lshl_add_u32 v2, v2, 7, v3
	v_and_b32_e32 v2, 0xfc00, v2
	s_or_b32 s76, s69, 0x400
	v_or_b32_e32 v144, 0x2000000, v2
	v_or_b32_e32 v2, s76, v252
	v_mul_u32_u24_e32 v3, 0x3e1, v2
	v_lshrrev_b32_e32 v3, 19, v3
	v_mul_i32_i24_e32 v4, 0xfffffdf0, v3
	v_add_lshl_u32 v2, v4, v2, 7
	v_and_b32_e32 v2, 0xfffffc00, v2
	s_or_b32 s77, s69, 0x500
	v_lshl_add_u32 v145, v3, 25, v2
	v_or_b32_e32 v2, s77, v252
	v_mov_b32_e32 v3, 0x7ffdf000
	v_lshl_add_u32 v2, v2, 7, v3
	v_and_b32_e32 v2, 0xfc00, v2
	s_or_b32 s78, s69, 0x600
	v_or_b32_e32 v146, 0x4000000, v2
	v_or_b32_e32 v2, s78, v252
	s_movk_i32 s79, 0x630
	v_cmp_gt_u32_e32 vcc, s79, v2
	s_and_b64 s[8:9], s[4:5], vcc
	v_writelane_b32 v255, s8, 2
	v_and_b32_e32 v6, 48, v252
	v_and_b32_e32 v3, 15, v0
	v_writelane_b32 v255, s9, 3
	v_lshrrev_b32_e32 v4, 4, v252
	v_readlane_b32 s17, v255, 7
	s_cmp_eq_u32 s17, 7
	s_cselect_b64 s[8:9], -1, 0
	s_lshr_b32 s1, s70, 7
	s_lshl_b32 s80, s1, 4
	s_add_i32 s2, s69, 0xf0
	s_lshl_b32 s1, s1, 6
	v_writelane_b32 v255, s2, 10
	s_add_i32 s2, s1, 0
	v_add_u32_e32 v148, s2, v6
	s_lshl_b32 s2, s17, 5
	s_and_b32 s16, s2, 32
	v_lshl_or_b32 v5, v4, 2, s80
	v_lshrrev_b32_e32 v8, 2, v0
	s_lshl_b32 s82, s0, 4
	v_or_b32_e32 v150, s16, v3
	s_movk_i32 s0, 0x44
	v_or_b32_e32 v7, s1, v3
	v_bitop3_b32 v8, v4, v8, 3 bitop3:0x78
	s_add_i32 s1, 0, 0x12540
	v_mul_lo_u32 v9, v5, s0
	v_or_b32_e32 v12, 16, v150
	v_lshl_add_u32 v149, v8, 4, s1
	v_bitop3_b32 v8, v4, v0, 7 bitop3:0x78
	v_add_u32_e32 v10, v9, v150
	v_bitop3_b32 v1, v4, v1, 4 bitop3:0x36
	v_add_u32_e32 v9, v9, v12
	v_lshlrev_b32_e32 v6, 1, v3
	v_cmp_eq_u32_e64 s[14:15], 3, v4
	v_lshlrev_b32_e32 v8, 4, v8
	v_lshl_add_u32 v151, v10, 2, 0
	v_lshlrev_b32_e32 v10, 7, v150
	v_lshlrev_b32_e32 v1, 4, v1
	v_lshl_add_u32 v153, v9, 2, 0
	v_lshlrev_b32_e32 v9, 7, v12
	v_lshlrev_b32_e32 v4, 5, v4
	v_or_b32_e32 v11, v10, v8
	v_or_b32_e32 v10, v10, v1
	v_or_b32_e32 v8, v9, v8
	v_or_b32_e32 v1, v9, v1
	v_lshlrev_b32_e32 v9, 6, v5
	v_bitop3_b32 v4, s16, v4, v6 bitop3:0x36
	v_and_or_b32 v4, v4, 56, v9
	v_or_b32_e32 v9, v4, v191
	v_lshlrev_b32_e32 v9, 1, v9
	s_add_i32 s89, 0, 0x12540
	s_add_i32 s90, 0, 0x16540
	s_add_i32 s91, 0, 0x18540
	s_add_i32 s92, 0, 0x14540
	v_add_u32_e32 v154, s89, v9
	v_add_u32_e32 v155, s90, v9
	v_add_u32_e32 v156, s91, v9
	v_add_u32_e32 v157, s92, v9
	v_or_b32_e32 v9, 1, v5
	v_lshlrev_b32_e32 v12, 6, v9
	v_lshlrev_b32_e32 v9, 3, v9
	v_bitop3_b32 v9, v9, s16, v6 bitop3:0x1e
	v_and_or_b32 v9, v9, 56, v12
	v_or_b32_e32 v12, v9, v191
	v_lshlrev_b32_e32 v12, 1, v12
	v_add_u32_e32 v158, s89, v12
	v_add_u32_e32 v159, s90, v12
	v_add_u32_e32 v160, s91, v12
	v_add_u32_e32 v161, s92, v12
	v_or_b32_e32 v12, 2, v5
	v_lshlrev_b32_e32 v13, 6, v12
	v_lshlrev_b32_e32 v12, 3, v12
	v_bitop3_b32 v12, v12, s16, v6 bitop3:0x1e
	v_and_or_b32 v12, v12, 56, v13
	v_or_b32_e32 v13, v12, v191
	v_lshlrev_b32_e32 v13, 1, v13
	v_or_b32_e32 v5, 3, v5
	v_add_u32_e32 v162, s89, v13
	v_add_u32_e32 v163, s90, v13
	v_add_u32_e32 v164, s91, v13
	v_add_u32_e32 v165, s92, v13
	v_lshlrev_b32_e32 v13, 6, v5
	v_lshlrev_b32_e32 v5, 3, v5
	v_bitop3_b32 v5, v5, s16, v6 bitop3:0x1e
	v_and_or_b32 v5, v5, 56, v13
	v_or_b32_e32 v6, v5, v191
	v_lshlrev_b32_e32 v6, 1, v6
	v_add_u32_e32 v166, s89, v6
	v_add_u32_e32 v167, s90, v6
	v_add_u32_e32 v168, s91, v6
	v_add_u32_e32 v169, s92, v6
	v_or_b32_e32 v6, s16, v7
	v_lshlrev_b32_e32 v170, 6, v6
	v_lshl_add_u32 v171, v6, 2, 0
	v_or_b32_e32 v6, 4, v191
	v_or_b32_e32 v4, v4, v6
	s_lshl_b32 s84, s17, 4
	v_lshlrev_b32_e32 v4, 1, v4
	s_load_dwordx4 s[16:19], s[6:7], 0xa8
	v_add_u32_e32 v172, s89, v4
	v_add_u32_e32 v173, s90, v4
	v_add_u32_e32 v174, s91, v4
	v_add_u32_e32 v175, s92, v4
	v_or_b32_e32 v4, v9, v6
	v_lshlrev_b32_e32 v4, 1, v4
	s_add_i32 s88, s2, 0
	v_add_u32_e32 v176, s89, v4
	v_add_u32_e32 v177, s90, v4
	v_add_u32_e32 v178, s91, v4
	v_add_u32_e32 v179, s92, v4
	v_or_b32_e32 v4, v12, v6
	s_add_i32 s83, s69, 0
	s_add_i32 s85, s88, 0x20540
	s_add_i32 s86, s88, 0x20d40
	s_add_i32 s87, s88, 0x21540
	s_add_i32 s88, s88, 0x21d40
	v_lshlrev_b32_e32 v4, 1, v4
	v_add_u32_e32 v180, s89, v4
	v_add_u32_e32 v181, s90, v4
	v_add_u32_e32 v182, s91, v4
	v_add_u32_e32 v183, s92, v4
	v_or_b32_e32 v4, v5, v6
	s_waitcnt lgkmcnt(0)
	s_add_u32 s93, s16, 0x20000
	v_mov_b32_e32 v5, 0x1f000
	v_add_u32_e32 v193, 0, v1
	v_mbcnt_lo_u32_b32 v1, -1, 0
	v_lshlrev_b32_e32 v4, 1, v4
	s_addc_u32 s94, s17, 0
	v_lshl_add_u32 v2, v2, 7, v5
	s_add_i32 s0, 0, 0x4000
	v_mbcnt_hi_u32_b32 v1, -1, v1
	v_add_u32_e32 v184, s89, v4
	v_add_u32_e32 v185, s90, v4
	v_add_u32_e32 v186, s91, v4
	v_add_u32_e32 v187, s92, v4
	v_or_b32_e32 v4, 0x400, v170
	v_and_b32_e32 v2, 0x1fc00, v2
	v_writelane_b32 v255, s0, 11
	s_mov_b32 s55, 0x20000
	v_and_or_b32 v1, v1, 64, v3
	v_and_b32_e32 v140, 0x70, v195
	s_mov_b32 s67, 0
	v_xor_b32_e32 v147, 0x1f8, v190
	v_cmp_gt_u32_e64 s[10:11], 16, v252
	v_cmp_lt_u32_e64 s[12:13], 31, v252
	v_lshl_add_u32 v152, v150, 2, 0
	v_or_b32_e32 v188, 0x4000000, v2
	s_mov_b32 s68, 0xbfb8aa3b
	s_mov_b32 s96, 0x2aaaaaab
	s_movk_i32 s97, 0xc0
	s_movk_i32 s64, 0x680
	s_mov_b32 s54, 0x4200400
	s_mov_b32 s26, 0x10000
	s_mov_b32 s58, 0x10000
	s_mov_b32 s59, s55
	v_mov_b32_e32 v5, 0
	s_movk_i32 s65, 0x208
	s_movk_i32 s34, 0x41f
	s_mov_b32 s62, 0x7ffffff0
	s_mov_b32 s63, s55
	s_mov_b32 s35, 0x10540
	v_add_u32_e32 v189, 0, v11
	v_add_u32_e32 v191, 0, v10
	v_add_u32_e32 v192, 0, v8
	s_mov_b32 s70, 0xbf60028a
	v_add_u32_e32 v194, v149, v4
	v_mov_b32_e32 v195, 0x3a27c5ac
	v_mov_b32_e32 v196, 1
	s_add_i32 s72, 0, 0x1ed40
	s_add_i32 s71, 0, 0x1f540
	s_add_i32 s33, 0, 0x1e540
	v_bfrev_b32_e32 v197, -2
	v_mov_b32_e32 v198, 0x9e20
	v_mov_b32_e32 v199, 0x5800
	v_mov_b32_e32 v200, 0x12800000
	v_mov_b32_e32 v201, 0x10800000
	v_lshlrev_b32_e32 v202, 2, v1
	v_lshrrev_b32_e32 v241, 2, v252
	v_lshrrev_b32_e32 v242, 4, v252
	v_and_b32_e32 v243, 3, v252
	v_xor_b32_e32 v242, v242, v243
	v_lshlrev_b32_e32 v242, 4, v242
	v_lshl_add_u32 v241, v241, 6, v242
	v_add_u32_e32 v253, 0x12540, v241
	v_lshl_add_u32 v241, s82, 8, v253
	v_lshrrev_b32_e32 v242, 3, v0
	v_and_b32_e32 v243, 7, v0
	v_lshlrev_b32_e32 v243, 3, v243
	v_lshrrev_b32_e32 v240, 2, v242
	v_and_b32_e32 v242, 3, v242
	v_lshlrev_b32_e32 v242, 1, v242
	v_or_b32_e32 v2, 0, v243
	v_and_b32_e32 v3, 15, v2
	v_xor_b32_e32 v3, v240, v3
	v_lshlrev_b32_e32 v3, 3, v3
	v_lshl_add_u32 v2, v2, 7, v3
	v_add_u32_e32 v244, v2, v242
	v_or_b32_e32 v2, 1, v243
	v_and_b32_e32 v3, 15, v2
	v_xor_b32_e32 v3, v240, v3
	v_lshlrev_b32_e32 v3, 3, v3
	v_lshl_add_u32 v2, v2, 7, v3
	v_add_u32_e32 v245, v2, v242
	v_or_b32_e32 v2, 2, v243
	v_and_b32_e32 v3, 15, v2
	v_xor_b32_e32 v3, v240, v3
	v_lshlrev_b32_e32 v3, 3, v3
	v_lshl_add_u32 v2, v2, 7, v3
	v_add_u32_e32 v246, v2, v242
	v_or_b32_e32 v2, 3, v243
	v_and_b32_e32 v3, 15, v2
	v_xor_b32_e32 v3, v240, v3
	v_lshlrev_b32_e32 v3, 3, v3
	v_lshl_add_u32 v2, v2, 7, v3
	v_add_u32_e32 v247, v2, v242
	v_or_b32_e32 v2, 4, v243
	v_and_b32_e32 v3, 15, v2
	v_xor_b32_e32 v3, v240, v3
	v_lshlrev_b32_e32 v3, 3, v3
	v_lshl_add_u32 v2, v2, 7, v3
	v_add_u32_e32 v248, v2, v242
	v_or_b32_e32 v2, 5, v243
	v_and_b32_e32 v3, 15, v2
	v_xor_b32_e32 v3, v240, v3
	v_lshlrev_b32_e32 v3, 3, v3
	v_lshl_add_u32 v2, v2, 7, v3
	v_add_u32_e32 v249, v2, v242
	v_or_b32_e32 v2, 6, v243
	v_and_b32_e32 v3, 15, v2
	v_xor_b32_e32 v3, v240, v3
	v_lshlrev_b32_e32 v3, 3, v3
	v_lshl_add_u32 v2, v2, 7, v3
	v_add_u32_e32 v250, v2, v242
	v_or_b32_e32 v2, 7, v243
	v_and_b32_e32 v3, 15, v2
	v_xor_b32_e32 v3, v240, v3
	v_lshlrev_b32_e32 v3, 3, v3
	v_lshl_add_u32 v2, v2, 7, v3
	v_add_u32_e32 v251, v2, v242
	v_and_b32_e32 v2, 63, v0
	v_lshrrev_b32_e32 v3, 6, v0
	v_lshlrev_b32_e32 v240, 10, v3
	v_lshl_add_u32 v234, v2, 1, v240
	v_lshlrev_b32_e32 v3, 1, v3
	v_and_b32_e32 v240, 15, v0
	v_xor_b32_e32 v242, v3, v240
	v_lshlrev_b32_e32 v243, 7, v2
	v_lshl_add_u32 v235, v242, 3, v243
	v_xor_b32_e32 v242, 1, v242
	v_lshl_add_u32 v236, v242, 3, v243
	v_readlane_b32 s95, v255, 9
	s_branch .LBB0_503

.LBB0_539:
	s_and_b32 s61, s23, 0xffff
	s_add_u32 s40, s22, 0x1000000
	s_addc_u32 s41, s23, 0
	s_and_b64 s[18:19], s[16:17], exec
	s_cselect_b32 s18, 0x780, 64
	s_lshl_b32 s19, s18, 10
	buffer_load_dwordx4 v[62:65], v1, s[52:55], s19 offen
	buffer_load_dwordx4 v[58:61], v203, s[52:55], s19 offen
	buffer_load_dwordx4 v[54:57], v204, s[52:55], s19 offen
	buffer_load_dwordx4 v[50:53], v205, s[52:55], s19 offen
	buffer_load_dwordx4 v[46:49], v206, s[52:55], s19 offen
	buffer_load_dwordx4 v[42:45], v207, s[52:55], s19 offen
	s_lshl_b32 s18, s18, 5
	buffer_load_dwordx4 v[38:41], v208, s[52:55], s19 offen
	buffer_load_dword v212, v209, s[56:59], s18 offen
	s_lshl_b32 s18, s95, 6
	s_lshl_b32 s2, s2, 15
	s_mov_b32 s60, s22
	s_xor_b32 s22, s18, 0x2000
	s_sub_i32 s50, s66, s2
	s_lshl_b32 s0, s0, 2
	s_ashr_i32 s23, s22, 31
	s_add_i32 s50, s50, 0x8000
	s_or_b32 s27, s0, 0xe00000
	s_and_b64 s[24:25], s[16:17], exec
	s_cselect_b32 s0, 0x200, 0
	s_add_i32 s0, s0, 0
	s_and_b64 s[24:25], s[16:17], exec
	s_cselect_b32 s19, 0, 0x200
	s_add_i32 s28, s19, 0
	s_or_b32 s29, s2, s66
	s_ashr_i32 s19, s18, 31
	s_lshl_b64 s[22:23], s[22:23], 2
	s_add_u32 s42, s93, s22
	s_addc_u32 s43, s94, s23
	s_lshl_b64 s[18:19], s[18:19], 2
	s_add_u32 s44, s93, s18
	s_addc_u32 s45, s94, s19
	s_lshl_b32 s2, s1, 1
	s_waitcnt vmcnt(12)
	v_lshlrev_b32_e32 v2, 2, v150
	s_add_u32 s46, s40, s2
	v_mov_b32_e32 v22, 0
	s_mov_b32 s51, 0
	v_add_u32_e32 v210, s0, v2
	v_add_u32_e32 v211, s28, v2
	s_addc_u32 s47, s41, 0
	v_mov_b32_e32 v23, v22
	v_mov_b32_e32 v24, v22
	v_mov_b32_e32 v25, v22
	v_mov_b32_e32 v26, v22
	v_mov_b32_e32 v27, v22
	v_mov_b32_e32 v28, v22
	v_mov_b32_e32 v29, v22
	v_mov_b32_e32 v30, v22
	v_mov_b32_e32 v31, v22
	v_mov_b32_e32 v32, v22
	v_mov_b32_e32 v33, v22
	v_mov_b32_e32 v34, v22
	v_mov_b32_e32 v35, v22
	v_mov_b32_e32 v36, v22
	v_mov_b32_e32 v37, v22
	s_waitcnt lgkmcnt(0)
	s_barrier
	v_and_b32_e32 v2, 63, v0
	v_lshlrev_b32_e32 v2, 2, v2
	v_add_u32_e32 v3, s0, v2
	ds_read_b32 v238, v3 offset:17920
	ds_read_b32 v240, v2 offset:18176
	v_add_u32_e32 v3, s28, v2
	ds_read_b32 v254, v3 offset:17920
	s_waitcnt lgkmcnt(0)
	ds_read_b128 v[154:157], v189
	ds_read_b128 v[158:161], v189 offset:8192
	ds_read_b128 v[162:165], v191
	ds_read_b128 v[166:169], v191 offset:8192
	ds_read_b128 v[172:175], v192
	ds_read_b128 v[176:179], v192 offset:8192
	ds_read_b128 v[180:183], v193
	ds_read_b128 v[184:187], v193 offset:8192
	s_waitcnt lgkmcnt(0)
	s_branch .LBB0_541

.LBB0_552:
	s_lshl_b32 s30, s51, 6
	s_sub_i32 s22, 0x800, s30
	s_sub_i32 s2, s30, 64
	v_mov_b32_e32 v90, v0
	s_cmp_lt_u32 s51, 17
	s_cbranch_scc1 .Lscan_skip_pload
	s_and_b64 s[18:19], s[16:17], exec
	v_mov_b32_e32 v2, v0
	s_cselect_b32 s18, s22, s2
	s_or_b32 s18, s18, 63
	v_ashrrev_i32_e32 v3, 3, v2
	v_sub_u32_e32 v4, s18, v3
	v_add_u32_e32 v3, s2, v3
	v_cndmask_b32_e64 v3, v3, v4, s[16:17]
	v_lshlrev_b32_e32 v2, 3, v2
	v_add_u32_e32 v4, s50, v3
	v_and_b32_e32 v2, 56, v2
	v_lshlrev_b32_e32 v66, 9, v4
	s_cmp_gt_u32 s51, 16
	v_or3_b32 v66, v66, s1, v2
	v_add_lshl_u32 v3, v3, s66, 9
	v_lshl_add_u32 v66, v66, 1, v200
	s_cselect_b64 vcc, -1, 0
	v_or3_b32 v2, v3, s1, v2
	v_cndmask_b32_e32 v66, v197, v66, vcc
	v_lshl_add_u32 v2, v2, 1, v201
	v_lshl_add_u32 v3, v4, 5, s27
	v_mov_b32_e32 v90, v0
	v_cndmask_b32_e32 v2, v197, v2, vcc
	v_cndmask_b32_e32 v3, v197, v3, vcc
	buffer_load_dwordx4 v[70:73], v66, s[60:63], 0 offen sc1
	s_nop 0
	buffer_load_dwordx4 v[66:69], v2, s[60:63], 0 offen
	buffer_load_dword v213, v3, s[60:63], 0 offen sc1
.Lscan_skip_pload:
	s_bitcmp0_b32 s51, 0
	ds_read_u16 v75, v234 offset:58688
	ds_read_u16 v79, v234 offset:59072
	ds_read_u16 v86, v234 offset:59200
	ds_read_u16 v87, v234 offset:59328
	ds_read_u16 v77, v234 offset:58944
	ds_read_u16 v80, v234 offset:58816
	ds_read_u16 v82, v234 offset:58432
	ds_read_u16 v83, v234 offset:58560
	s_waitcnt lgkmcnt(7)
	v_lshlrev_b32_e32 v76, 16, v75
	ds_read_u16 v75, v234 offset:59456
	ds_read_u16 v3, v234 offset:59584
	s_waitcnt lgkmcnt(5)
	v_lshlrev_b32_e32 v78, 16, v77
	s_waitcnt lgkmcnt(4)
	v_lshlrev_b32_e32 v77, 16, v80
	s_waitcnt lgkmcnt(2)
	v_lshlrev_b32_e32 v83, 16, v83
	v_lshlrev_b32_e32 v82, 16, v82
	v_pk_mov_b32 v[84:85], v[82:83], v[76:77] op_sel:[1,0]
	v_mov_b32_e32 v80, v77
	v_mov_b32_e32 v81, v78
	v_pk_mul_f32 v[84:85], v[240:241], v[84:85] op_sel_hi:[0, 1]
	s_waitcnt lgkmcnt(0)
	v_pk_fma_f32 v[82:83], v[238:239], v[82:83], v[84:85] op_sel_hi:[0, 1, 1]
	v_pk_mul_f32 v[80:81], v[240:241], v[80:81] op_sel_hi:[0, 1]
	v_lshlrev_b32_e32 v79, 16, v79
	v_pk_fma_f32 v[82:83], v[254:255], v[76:77], v[82:83] op_sel_hi:[0, 1, 1]
	v_pk_fma_f32 v[76:77], v[238:239], v[76:77], v[80:81] op_sel_hi:[0, 1, 1]
	v_lshlrev_b32_e32 v80, 16, v86
	v_lshlrev_b32_e32 v81, 16, v87
	v_lshlrev_b32_e32 v87, 16, v75
	v_mov_b32_e32 v86, v81
	v_pk_mov_b32 v[88:89], v[78:79], v[80:81] op_sel:[1,0]
	v_mov_b32_e32 v84, v87
	v_pk_mul_f32 v[88:89], v[240:241], v[88:89] op_sel_hi:[0, 1]
	v_pk_mul_f32 v[86:87], v[240:241], v[86:87] op_sel_hi:[0, 1]
	s_cselect_b32 s18, s35, 0x22540
	s_cmp_lg_u32 s51, 31
	v_pk_fma_f32 v[76:77], v[254:255], v[78:79], v[76:77] op_sel_hi:[0, 1, 1]
	v_lshlrev_b32_e32 v85, 16, v3
	v_pk_fma_f32 v[78:79], v[238:239], v[78:79], v[88:89] op_sel_hi:[0, 1, 1]
	v_pk_fma_f32 v[2:3], v[238:239], v[80:81], v[86:87] op_sel_hi:[0, 1, 1]
	s_cselect_b64 s[48:49], -1, 0
	s_add_i32 s31, s18, 0
	v_pk_fma_f32 v[78:79], v[254:255], v[80:81], v[78:79] op_sel_hi:[0, 1, 1]
	v_pk_fma_f32 v[2:3], v[254:255], v[84:85], v[2:3] op_sel_hi:[0, 1, 1]
	v_cvt_pk_bf16_f32 v75, v76, v77
	v_cvt_pk_bf16_f32 v74, v82, v83
	v_add_u32_e32 v80, s31, v235
	ds_write_b64 v80, v[74:75]
	v_cvt_pk_bf16_f32 v75, v2, v3
	v_cvt_pk_bf16_f32 v74, v78, v79
	v_add_u32_e32 v2, s31, v236
	ds_write_b64 v2, v[74:75]
	v_add_u32_e32 v2, 0x5800, v151
	ds_read2_b32 v[104:105], v2 offset1:16
	ds_read2_b32 v[118:119], v2 offset0:68 offset1:136
	v_add_u32_e32 v2, 0x9c00, v151
	ds_read2_b32 v[106:107], v2 offset0:136 offset1:152
	v_add_u32_e32 v2, 0x9e00, v151
	ds_read2_b32 v[120:121], v2 offset0:76 offset1:144
	v_add_u32_e32 v2, 0x5a00, v151
	ds_read2_b32 v[128:129], v2 offset0:76 offset1:144
	v_add_u32_e32 v2, 0xa000, v151
	v_add_u32_e32 v4, 0x4000, v152
	ds_read2_b32 v[126:127], v2 offset0:84 offset1:152
	ds_read_b128 v[74:77], v148 offset:20224
	ds_read_b32 v219, v151 offset:23888
	ds_read_b32 v3, v153 offset:41840
	ds_read_b32 v221, v151 offset:41840
	v_add_u32_e32 v2, 0x4000, v210
	ds_read2_b32 v[94:95], v4 offset0:64 offset1:80
	v_add_u32_e32 v4, 0x4000, v211
	ds_read2_b32 v[90:91], v2 offset1:16
	ds_read2_b32 v[92:93], v4 offset1:16
	ds_read2_b32 v[86:87], v2 offset0:192 offset1:208
	ds_read_b32 v99, v153 offset:23888
	s_waitcnt vmcnt(11)
	v_mfma_f32_16x16x32_bf16 v[78:81], v[10:13], v[154:157], 0
	v_add_u32_e32 v2, 0x4400, v152
	ds_read2_b32 v[102:103], v2 offset1:16
	ds_read2_b32 v[100:101], v4 offset0:192 offset1:208
	v_add_u32_e32 v2, 0x4800, v152
	s_waitcnt vmcnt(10)
	v_mfma_f32_16x16x32_bf16 v[136:139], v[6:9], v[162:165], v[78:81]
	ds_read2_b32 v[96:97], v2 offset0:128 offset1:144
	ds_read2_b32 v[88:89], v2 offset0:192 offset1:208
	s_nop 0
	v_add_u32_e32 v2, 0x4c00, v152
	ds_read2_b32 v[132:133], v2 offset0:64 offset1:80
	s_waitcnt vmcnt(9)
	v_mfma_f32_16x16x32_bf16 v[82:85], v[18:21], v[158:161], 0
	s_add_i32 s81, s30, 64
	s_sub_i32 s2, 0x780, s30
	s_cmp_eq_u32 s51, 31
	s_waitcnt vmcnt(8)
	v_mfma_f32_16x16x32_bf16 v[214:217], v[14:17], v[166:169], v[82:85]
	ds_read2_b32 v[116:117], v2 offset0:128 offset1:144
	s_nop 0
	v_add_u32_e32 v2, 0x5800, v153
	ds_read2_b32 v[112:113], v2 offset0:68 offset1:136
	v_mfma_f32_16x16x32_bf16 v[10:13], v[10:13], v[172:175], 0
	v_add_u32_e32 v2, 0x9e00, v153
	ds_read2_b32 v[108:109], v2 offset0:76 offset1:144
	v_add_u32_e32 v2, 0x5a00, v153
	v_mfma_f32_16x16x32_bf16 v[82:85], v[6:9], v[180:183], v[10:13]
	s_cselect_b32 s23, 0x7c0, s81
	ds_read2_b32 v[114:115], v2 offset0:76 offset1:144
	v_mfma_f32_16x16x32_bf16 v[10:13], v[18:21], v[176:179], 0
	v_add_u32_e32 v2, 0xa000, v153
	s_cselect_b32 s24, 31, s2
	s_and_b64 s[18:19], s[16:17], exec
	ds_read2_b32 v[110:111], v2 offset0:84 offset1:152
	v_mov_b32_e32 v2, v0
	s_cselect_b32 s18, s24, s23
	s_or_b32 s18, s18, 63
	v_and_or_b32 v4, v2, 15, s80
	v_mfma_f32_16x16x32_bf16 v[78:81], v[14:17], v[184:187], v[10:13]
	v_sub_u32_e32 v6, s18, v4
	v_add_u32_e32 v4, s23, v4
	v_cndmask_b32_e64 v6, v4, v6, s[16:17]
	v_ashrrev_i32_e32 v7, 31, v6
	v_lshl_add_u64 v[6:7], v[6:7], 0, s[66:67]
	v_lshlrev_b64 v[6:7], 7, v[6:7]
	v_lshl_add_u64 v[8:9], s[36:37], 0, v[6:7]
	v_and_b32_e32 v4, 48, v2
	v_lshl_add_u64 v[6:7], s[38:39], 0, v[6:7]
	v_lshl_add_u64 v[14:15], v[6:7], 0, v[4:5]
	s_waitcnt lgkmcnt(5)
	v_pk_add_f32 v[6:7], v[132:133], v[136:137] op_sel_hi:[0,1]
	v_exp_f32_e32 v6, v6
	v_exp_f32_e32 v7, v7
	v_pk_add_f32 v[10:11], v[132:133], v[138:139] op_sel_hi:[0,1]
	v_exp_f32_e32 v10, v10
	v_exp_f32_e32 v11, v11
	v_pk_add_f32 v[6:7], v[6:7], 1.0 op_sel_hi:[1,0]
	v_lshl_add_u64 v[8:9], v[8:9], 0, v[4:5]
	v_rcp_f32_e32 v16, v6
	v_rcp_f32_e32 v17, v7
	v_pk_add_f32 v[6:7], v[10:11], 1.0 op_sel_hi:[1,0]
	s_waitcnt lgkmcnt(4)
	v_pk_add_f32 v[214:215], v[116:117], v[214:215] op_sel_hi:[0,1]
	v_rcp_f32_e32 v18, v6
	v_rcp_f32_e32 v19, v7
	v_pk_mul_f32 v[222:223], v[16:17], s[70:71] op_sel_hi:[1,0]
	global_load_dwordx4 v[10:13], v[8:9], off
	s_nop 0
	global_load_dwordx4 v[6:9], v[8:9], off offset:64
	v_pk_fma_f32 v[224:225], v[16:17], s[70:71], v[222:223] op_sel:[0,0,1] op_sel_hi:[1,0,0]
	v_mul_f32_e32 v2, 0xbf60028a, v19
	v_pk_fma_f32 v[226:227], v[18:19], s[70:71], v[224:225] op_sel_hi:[1,0,1]
	global_load_dwordx4 v[18:21], v[14:15], off
	s_nop 0
	global_load_dwordx4 v[14:17], v[14:15], off offset:64
	v_pk_add_f32 v[228:229], v[2:3], v[226:227] op_sel_hi:[0,1]
	v_mov_b32_e32 v136, v228
	v_mov_b32_e32 v138, v228
	s_nop 1
	v_permlane16_swap_b32_e32 v136, v138
	v_mov_b32_e32 v137, v136
	v_mov_b32_e32 v139, v138
	s_nop 1
	v_permlane32_swap_b32_e32 v136, v137
	v_permlane32_swap_b32_e32 v138, v139
	v_exp_f32_e32 v214, v214
	v_exp_f32_e32 v215, v215
	v_pk_add_f32 v[216:217], v[116:117], v[216:217] op_sel_hi:[0,1]
	v_exp_f32_e32 v216, v216
	v_exp_f32_e32 v217, v217
	v_cndmask_b32_e64 v2, v136, 0, s[10:11]
	v_cndmask_b32_e64 v4, 0, v138, s[12:13]
	v_pk_add_f32 v[214:215], v[214:215], 1.0 op_sel_hi:[1,0]
	v_add_f32_e32 v2, v2, v4
	v_cndmask_b32_e64 v4, 0, v137, s[14:15]
	v_rcp_f32_e32 v214, v214
	v_rcp_f32_e32 v215, v215
	v_add_f32_e32 v2, v2, v4
	v_mov_b32_e32 v223, v224
	v_pk_add_f32 v[216:217], v[216:217], 1.0 op_sel_hi:[1,0]
	v_mov_b32_e32 v122, v106
	v_mov_b32_e32 v123, v120
	v_mov_b32_e32 v130, v121
	v_pk_add_f32 v[224:225], v[222:223], v[2:3] op_sel_hi:[1,0]
	v_mov_b32_e32 v227, v228
	v_rcp_f32_e32 v216, v216
	v_rcp_f32_e32 v217, v217
	v_pk_mul_f32 v[120:121], v[120:121], v[102:103] op_sel_hi:[1,0]
	v_mov_b32_e32 v131, v126
	v_pk_add_f32 v[226:227], v[226:227], v[2:3] op_sel_hi:[1,0]
	v_exp_f32_e32 v228, v224
	v_sub_f32_e32 v2, v224, v222
	v_pk_fma_f32 v[120:121], v[122:123], v[86:87], v[120:121] op_sel_hi:[1,0,1]
	v_pk_mul_f32 v[122:123], v[126:127], v[102:103] op_sel_hi:[1,0]
	v_exp_f32_e32 v222, v2
	v_pk_fma_f32 v[120:121], v[130:131], v[100:101], v[120:121] op_sel_hi:[1,0,1]
	v_pk_fma_f32 v[122:123], v[130:131], v[86:87], v[122:123] op_sel_hi:[1,0,1]
	v_pk_add_f32 v[130:131], v[214:215], -1.0 op_sel_hi:[1,0]
	v_exp_f32_e32 v229, v225
	v_exp_f32_e32 v230, v226
	v_exp_f32_e64 v232, -v224
	v_exp_f32_e64 v233, -v225
	v_pk_mul_f32 v[130:131], v[88:89], v[130:131] op_sel_hi:[0,1]
	v_mov_b32_e32 v220, v127
	v_pk_mul_f32 v[126:127], v[96:97], v[120:121] op_sel_hi:[0,1]
	v_pk_fma_f32 v[120:121], v[120:121], v[130:131], v[120:121]
	v_pk_add_f32 v[130:131], v[216:217], -1.0 op_sel_hi:[1,0]
	v_mov_b32_e32 v124, v104
	v_mov_b32_e32 v125, v118
	v_mov_b32_e32 v134, v119
	v_exp_f32_e32 v231, v227
	v_exp_f32_e64 v226, -v226
	v_exp_f32_e64 v227, -v227
	v_mov_b32_e32 v223, v228
	v_pk_mul_f32 v[118:119], v[118:119], v[94:95] op_sel_hi:[1,0]
	v_pk_fma_f32 v[122:123], v[220:221], v[100:101], v[122:123] op_sel_hi:[1,0,1]
	v_pk_mul_f32 v[126:127], v[74:75], v[126:127]
	v_pk_mul_f32 v[130:131], v[88:89], v[130:131] op_sel_hi:[0,1]
	v_mov_b32_e32 v135, v128
	v_mov_b32_e32 v218, v129
	v_pk_fma_f32 v[118:119], v[124:125], v[90:91], v[118:119] op_sel_hi:[1,0,1]
	v_pk_mul_f32 v[124:125], v[128:129], v[94:95] op_sel_hi:[1,0]
	v_pk_mul_f32 v[128:129], v[96:97], v[122:123] op_sel_hi:[0,1]
	v_pk_fma_f32 v[122:123], v[122:123], v[130:131], v[122:123]
	v_pk_mul_f32 v[130:131], v[126:127], v[222:223] neg_lo:[0,1] neg_hi:[0,1]
	v_pk_mul_f32 v[126:127], v[126:127], v[214:215]
	v_mov_b32_e32 v224, v229
	v_mov_b32_e32 v225, v230
	v_pk_fma_f32 v[118:119], v[134:135], v[92:93], v[118:119] op_sel_hi:[1,0,1]
	v_pk_mul_f32 v[128:129], v[76:77], v[128:129]
	v_pk_mul_f32 v[126:127], v[126:127], v[232:233]
	v_pk_fma_f32 v[124:125], v[134:135], v[90:91], v[124:125] op_sel_hi:[1,0,1]
	v_pk_mul_f32 v[134:135], v[128:129], v[224:225] neg_lo:[0,1] neg_hi:[0,1]
	v_pk_mul_f32 v[128:129], v[128:129], v[216:217]
	v_pk_mul_f32 v[120:121], v[120:121], v[232:233]
	v_pk_mul_f32 v[118:119], v[118:119], v[228:229]
	v_pk_fma_f32 v[124:125], v[218:219], v[92:93], v[124:125] op_sel_hi:[1,0,1]
	v_pk_mul_f32 v[128:129], v[128:129], v[226:227]
	v_pk_mul_f32 v[122:123], v[122:123], v[226:227]
	v_pk_mul_f32 v[124:125], v[124:125], v[230:231]
	v_cvt_pk_bf16_f32 v125, v124, v125
	v_cvt_pk_bf16_f32 v124, v118, v119
	v_cvt_pk_bf16_f32 v118, v126, v127
	v_cvt_pk_bf16_f32 v119, v128, v129
	v_cvt_pk_bf16_f32 v120, v120, v121
	v_cvt_pk_bf16_f32 v121, v122, v123
	v_cvt_pk_bf16_f32 v122, v130, v131
	v_cvt_pk_bf16_f32 v123, v134, v135
	v_add_u32_e32 v2, v149, v170
	ds_write_b128 v2, v[118:121] offset:32768
	ds_write_b128 v2, v[122:125]
	s_and_saveexec_b64 s[18:19], s[10:11]
	s_cbranch_execz .LBB0_554
	s_waitcnt lgkmcnt(2)
	v_pk_add_f32 v[118:119], v[138:139], v[136:137]
	s_nop 0
	v_add_f32_e32 v2, v118, v119
	v_exp_f32_e32 v2, v2
	ds_write_b32 v171, v2 offset:20992
.LBB0_554:
	s_or_b64 exec, exec, s[18:19]
	v_mov_b32_e32 v2, v133
	v_pk_add_f32 v[82:83], v[2:3], v[82:83] op_sel_hi:[0,1]
	v_exp_f32_e32 v82, v82
	v_exp_f32_e32 v83, v83
	v_pk_add_f32 v[84:85], v[2:3], v[84:85] op_sel_hi:[0,1]
	v_exp_f32_e32 v84, v84
	v_exp_f32_e32 v85, v85
	v_pk_add_f32 v[82:83], v[82:83], 1.0 op_sel_hi:[1,0]
	v_rcp_f32_e32 v82, v82
	v_rcp_f32_e32 v83, v83
	v_pk_add_f32 v[84:85], v[84:85], 1.0 op_sel_hi:[1,0]
	v_rcp_f32_e32 v84, v84
	v_rcp_f32_e32 v85, v85
	v_pk_mul_f32 v[122:123], v[82:83], s[70:71] op_sel_hi:[1,0]
	v_pk_fma_f32 v[124:125], v[82:83], s[70:71], v[122:123] op_sel:[0,0,1] op_sel_hi:[1,0,0]
	v_mul_f32_e32 v2, 0xbf60028a, v85
	v_pk_fma_f32 v[126:127], v[84:85], s[70:71], v[124:125] op_sel_hi:[1,0,1]
	v_mov_b32_e32 v123, v124
	v_pk_add_f32 v[128:129], v[2:3], v[126:127] op_sel_hi:[0,1]
	v_mov_b32_e32 v82, v128
	v_mov_b32_e32 v84, v128
	s_nop 1
	v_permlane16_swap_b32_e32 v82, v84
	v_mov_b32_e32 v83, v82
	v_mov_b32_e32 v85, v84
	s_nop 1
	v_permlane32_swap_b32_e32 v82, v83
	v_permlane32_swap_b32_e32 v84, v85
	v_mov_b32_e32 v127, v128
	v_mov_b32_e32 v104, v105
	v_cndmask_b32_e64 v4, v82, 0, s[10:11]
	v_cndmask_b32_e64 v86, 0, v84, s[12:13]
	v_add_f32_e32 v4, v4, v86
	v_cndmask_b32_e64 v86, 0, v83, s[14:15]
	v_add_f32_e32 v4, v4, v86
	v_pk_add_f32 v[124:125], v[122:123], v[4:5] op_sel_hi:[1,0]
	v_pk_add_f32 v[126:127], v[126:127], v[4:5] op_sel_hi:[1,0]
	v_sub_f32_e32 v4, v124, v122
	v_exp_f32_e32 v122, v4
	v_mov_b32_e32 v4, v117
	v_pk_add_f32 v[80:81], v[4:5], v[80:81] op_sel_hi:[0,1]
	v_pk_add_f32 v[78:79], v[4:5], v[78:79] op_sel_hi:[0,1]
	v_exp_f32_e32 v80, v80
	v_exp_f32_e32 v81, v81
	v_exp_f32_e32 v78, v78
	v_exp_f32_e32 v79, v79
	v_mov_b32_e32 v86, v95
	v_mov_b32_e32 v105, v112
	v_mov_b32_e32 v118, v113
	v_mov_b32_e32 v119, v114
	v_pk_add_f32 v[80:81], v[80:81], 1.0 op_sel_hi:[1,0]
	v_mov_b32_e32 v4, v91
	v_pk_mul_f32 v[90:91], v[112:113], v[86:87] op_sel_hi:[1,0]
	v_mov_b32_e32 v88, v93
	v_pk_mul_f32 v[92:93], v[114:115], v[86:87] op_sel_hi:[1,0]
	v_mov_b32_e32 v86, v103
	v_mov_b32_e32 v106, v107
	v_mov_b32_e32 v107, v108
	v_mov_b32_e32 v98, v115
	v_pk_add_f32 v[78:79], v[78:79], 1.0 op_sel_hi:[1,0]
	v_rcp_f32_e32 v80, v80
	v_rcp_f32_e32 v81, v81
	v_pk_fma_f32 v[90:91], v[104:105], v[4:5], v[90:91] op_sel_hi:[1,0,1]
	v_pk_fma_f32 v[92:93], v[118:119], v[4:5], v[92:93] op_sel_hi:[1,0,1]
	v_mov_b32_e32 v4, v87
	v_pk_mul_f32 v[94:95], v[108:109], v[86:87] op_sel_hi:[1,0]
	v_mov_b32_e32 v120, v109
	v_mov_b32_e32 v121, v110
	v_exp_f32_e32 v128, v124
	v_rcp_f32_e32 v78, v78
	v_rcp_f32_e32 v79, v79
	v_pk_fma_f32 v[90:91], v[118:119], v[88:89], v[90:91] op_sel_hi:[1,0,1]
	v_pk_fma_f32 v[92:93], v[98:99], v[88:89], v[92:93] op_sel_hi:[1,0,1]
	v_pk_fma_f32 v[94:95], v[106:107], v[4:5], v[94:95] op_sel_hi:[1,0,1]
	v_mov_b32_e32 v88, v101
	v_pk_mul_f32 v[86:87], v[110:111], v[86:87] op_sel_hi:[1,0]
	v_mov_b32_e32 v2, v111
	v_pk_fma_f32 v[94:95], v[120:121], v[88:89], v[94:95] op_sel_hi:[1,0,1]
	v_pk_fma_f32 v[86:87], v[120:121], v[4:5], v[86:87] op_sel_hi:[1,0,1]
	v_mov_b32_e32 v4, v97
	v_exp_f32_e32 v129, v125
	v_exp_f32_e32 v130, v126
	v_exp_f32_e64 v132, -v124
	v_exp_f32_e64 v133, -v125
	v_pk_fma_f32 v[2:3], v[2:3], v[88:89], v[86:87] op_sel_hi:[1,0,1]
	v_pk_mul_f32 v[86:87], v[4:5], v[94:95] op_sel_hi:[0,1]
	v_pk_mul_f32 v[74:75], v[74:75], v[86:87]
	v_pk_mul_f32 v[86:87], v[4:5], v[2:3] op_sel_hi:[0,1]
	v_mov_b32_e32 v4, v89
	v_pk_add_f32 v[88:89], v[80:81], -1.0 op_sel_hi:[1,0]
	v_exp_f32_e32 v131, v127
	v_exp_f32_e64 v126, -v126
	v_exp_f32_e64 v127, -v127
	v_mov_b32_e32 v123, v128
	v_pk_mul_f32 v[76:77], v[76:77], v[86:87]
	v_pk_add_f32 v[86:87], v[78:79], -1.0 op_sel_hi:[1,0]
	v_pk_mul_f32 v[88:89], v[4:5], v[88:89] op_sel_hi:[0,1]
	v_pk_mul_f32 v[86:87], v[4:5], v[86:87] op_sel_hi:[0,1]
	v_pk_fma_f32 v[2:3], v[2:3], v[88:89], v[2:3]
	v_pk_mul_f32 v[88:89], v[74:75], v[122:123] neg_lo:[0,1] neg_hi:[0,1]
	v_pk_mul_f32 v[74:75], v[74:75], v[78:79]
	v_mov_b32_e32 v124, v129
	v_mov_b32_e32 v125, v130
	v_pk_fma_f32 v[86:87], v[94:95], v[86:87], v[94:95]
	v_pk_mul_f32 v[74:75], v[74:75], v[132:133]
	v_pk_mul_f32 v[94:95], v[76:77], v[124:125] neg_lo:[0,1] neg_hi:[0,1]
	v_pk_mul_f32 v[76:77], v[76:77], v[80:81]
	v_pk_mul_f32 v[78:79], v[86:87], v[132:133]
	v_pk_mul_f32 v[80:81], v[90:91], v[128:129]
	v_pk_mul_f32 v[76:77], v[76:77], v[126:127]
	v_pk_mul_f32 v[2:3], v[2:3], v[126:127]
	v_pk_mul_f32 v[86:87], v[92:93], v[130:131]
	v_cvt_pk_bf16_f32 v74, v74, v75
	v_cvt_pk_bf16_f32 v75, v76, v77
	v_cvt_pk_bf16_f32 v76, v78, v79
	v_cvt_pk_bf16_f32 v77, v2, v3
	v_cvt_pk_bf16_f32 v78, v88, v89
	v_cvt_pk_bf16_f32 v79, v94, v95
	v_cvt_pk_bf16_f32 v80, v80, v81
	v_cvt_pk_bf16_f32 v81, v86, v87
	ds_write_b128 v194, v[74:77] offset:32768
	ds_write_b128 v194, v[78:81]
	s_and_saveexec_b64 s[18:19], s[10:11]
	s_cbranch_execz .LBB0_556
	s_waitcnt lgkmcnt(2)
	v_pk_add_f32 v[2:3], v[84:85], v[82:83]
	s_nop 0
	v_add_f32_e32 v2, v2, v3
	v_exp_f32_e32 v2, v2
	ds_write_b32 v171, v2 offset:21056

.LBB0_561:
	s_and_b32 s18, s24, 1
	s_cmp_eq_u32 s18, 0
	s_cselect_b32 s19, s35, 0x22540
	s_lshl_b32 s18, s18, 8
	s_add_i32 s18, s18, 0
	v_lshl_add_u32 v78, v81, 2, s18
	v_add_u32_e32 v3, s19, v244
	v_add_u32_e32 v108, s19, v245
	v_add_u32_e32 v107, s19, v246
	v_add_u32_e32 v100, s19, v247
	v_add_u32_e32 v101, s19, v248
	v_add_u32_e32 v102, s19, v249
	v_add_u32_e32 v103, s19, v250
	v_add_u32_e32 v81, s19, v251
	v_lshl_add_u32 v106, v80, 2, 0
	ds_read_b32 v78, v78 offset:20480
	s_waitcnt lgkmcnt(14)
	ds_read_b128 v[82:85], v106 offset:18688
	ds_read_b128 v[86:89], v106 offset:22272
	ds_read_b128 v[90:93], v106 offset:18704
	ds_read_u16 v102, v102
	ds_read_u16 v120, v103
	ds_read_u16 v81, v81
	ds_read_u16 v103, v101
	ds_read_u16 v109, v100
	s_waitcnt lgkmcnt(9)
	v_lshlrev_b32_e32 v94, 16, v77
	v_and_b32_e32 v95, 0xffff0000, v77
	s_waitcnt vmcnt(6)
	v_lshlrev_b32_e32 v96, 16, v73
	v_and_b32_e32 v97, 0xffff0000, v73
	v_pk_add_f32 v[98:99], v[96:97], v[94:95]
	v_lshlrev_b32_e32 v94, 16, v76
	v_and_b32_e32 v95, 0xffff0000, v76
	v_lshlrev_b32_e32 v96, 16, v72
	v_and_b32_e32 v97, 0xffff0000, v72
	v_lshlrev_b32_e32 v110, 16, v74
	v_and_b32_e32 v111, 0xffff0000, v74
	v_lshlrev_b32_e32 v112, 16, v70
	v_and_b32_e32 v113, 0xffff0000, v70
	v_pk_add_f32 v[72:73], v[96:97], v[94:95]
	v_lshlrev_b32_e32 v94, 16, v75
	v_and_b32_e32 v95, 0xffff0000, v75
	v_lshlrev_b32_e32 v96, 16, v71
	v_and_b32_e32 v97, 0xffff0000, v71
	v_pk_add_f32 v[70:71], v[112:113], v[110:111]
	s_waitcnt lgkmcnt(4)
	v_lshlrev_b32_e32 v101, 16, v102
	s_waitcnt lgkmcnt(1)
	v_lshlrev_b32_e32 v100, 16, v103
	s_waitcnt vmcnt(5)
	v_lshlrev_b32_e32 v102, 16, v68
	v_and_b32_e32 v103, 0xffff0000, v68
	v_pk_add_f32 v[104:105], v[96:97], v[94:95]
	ds_read_u16 v68, v107
	s_waitcnt lgkmcnt(1)
	v_lshlrev_b32_e32 v107, 16, v109
	ds_read_b128 v[94:97], v106 offset:22288
	ds_read_u16 v3, v3
	ds_read_u16 v114, v108
	v_lshlrev_b32_e32 v108, 16, v67
	v_and_b32_e32 v109, 0xffff0000, v67
	v_add_f32_e32 v67, 0, v70
	v_add_f32_e32 v67, v71, v67
	v_add_f32_e32 v67, v104, v67
	v_add_f32_e32 v67, v105, v67
	v_add_f32_e32 v67, v72, v67
	v_add_f32_e32 v67, v73, v67
	v_add_f32_e32 v67, v98, v67
	v_add_f32_e32 v67, v99, v67
	s_waitcnt lgkmcnt(3)
	v_lshlrev_b32_e32 v106, 16, v68
	s_waitcnt lgkmcnt(0)
	v_lshlrev_b32_e32 v111, 16, v114
	v_add_f32_dpp v67, v67, v67 quad_perm:[1,0,3,2] row_mask:0xf bank_mask:0xf bound_ctrl:1
	s_waitcnt vmcnt(4)
	v_add_f32_e32 v78, v78, v213
	v_lshlrev_b32_e32 v110, 16, v3
	v_add_f32_dpp v67, v67, v67 quad_perm:[2,3,0,1] row_mask:0xf bank_mask:0xf bound_ctrl:1
	v_ashrrev_i32_e32 v3, 31, v2
	s_nop 0
	v_add_f32_dpp v67, v67, v67 row_half_mirror row_mask:0xf bank_mask:0xf bound_ctrl:1
	v_mul_f32_e32 v68, 0x3c800000, v67
	v_pk_add_f32 v[70:71], v[70:71], v[68:69] op_sel_hi:[1,0] neg_lo:[0,1] neg_hi:[0,1]
	v_pk_add_f32 v[104:105], v[104:105], v[68:69] op_sel_hi:[1,0] neg_lo:[0,1] neg_hi:[0,1]
	v_pk_mul_f32 v[112:113], v[70:71], v[70:71]
	v_pk_mul_f32 v[114:115], v[104:105], v[104:105]
	v_add_f32_e32 v67, v112, v113
	v_pk_add_f32 v[72:73], v[72:73], v[68:69] op_sel_hi:[1,0] neg_lo:[0,1] neg_hi:[0,1]
	v_add_f32_e32 v67, v114, v67
	v_pk_mul_f32 v[116:117], v[72:73], v[72:73]
	v_add_f32_e32 v67, v115, v67
	v_pk_add_f32 v[98:99], v[98:99], v[68:69] op_sel_hi:[1,0] neg_lo:[0,1] neg_hi:[0,1]
	v_add_f32_e32 v67, v116, v67
	v_pk_mul_f32 v[118:119], v[98:99], v[98:99]
	v_add_f32_e32 v67, v117, v67
	v_add_f32_e32 v67, v118, v67
	v_add_f32_e32 v67, v119, v67
	v_lshlrev_b32_e32 v112, 16, v66
	v_and_b32_e32 v113, 0xffff0000, v66
	v_add_f32_dpp v67, v67, v67 quad_perm:[1,0,3,2] row_mask:0xf bank_mask:0xf bound_ctrl:1
	s_nop 1
	v_add_f32_dpp v67, v67, v67 quad_perm:[2,3,0,1] row_mask:0xf bank_mask:0xf bound_ctrl:1
	s_nop 1
	v_add_f32_dpp v67, v67, v67 row_half_mirror row_mask:0xf bank_mask:0xf bound_ctrl:1
	v_fmamk_f32 v67, v67, 0x3c800000, v195
	v_rsq_f32_e32 v68, v67
	s_nop 0
	v_pk_mul_f32 v[66:67], v[70:71], v[68:69] op_sel_hi:[1,0]
	v_pk_mul_f32 v[70:71], v[104:105], v[68:69] op_sel_hi:[1,0]
	v_pk_fma_f32 v[66:67], v[86:87], v[66:67], v[82:83]
	v_pk_fma_f32 v[70:71], v[88:89], v[70:71], v[84:85]
	v_pk_fma_f32 v[66:67], v[78:79], v[110:111], v[66:67] op_sel_hi:[0,1,1]
	v_pk_fma_f32 v[70:71], v[78:79], v[106:107], v[70:71] op_sel_hi:[0,1,1]
	v_pk_mul_f32 v[66:67], v[66:67], v[112:113]
	v_pk_mul_f32 v[70:71], v[70:71], v[108:109]
	v_pk_mul_f32 v[72:73], v[72:73], v[68:69] op_sel_hi:[1,0]
	v_lshlrev_b32_e32 v84, 16, v69
	v_and_b32_e32 v85, 0xffff0000, v69
	v_pk_mul_f32 v[68:69], v[98:99], v[68:69] op_sel_hi:[1,0]
	v_pk_fma_f32 v[72:73], v[94:95], v[72:73], v[90:91]
	v_lshlrev_b32_e32 v83, 16, v81
	v_lshlrev_b32_e32 v82, 16, v120
	v_pk_fma_f32 v[68:69], v[96:97], v[68:69], v[92:93]
	v_cvt_pk_bf16_f32 v66, v66, v67
	v_cvt_pk_bf16_f32 v67, v70, v71
	v_lshl_add_u64 v[70:71], v[2:3], 0, s[66:67]
	v_pk_fma_f32 v[72:73], v[78:79], v[100:101], v[72:73] op_sel_hi:[0,1,1]
	v_pk_fma_f32 v[68:69], v[78:79], v[82:83], v[68:69] op_sel_hi:[0,1,1]
	v_lshlrev_b64 v[70:71], 11, v[70:71]
	v_pk_mul_f32 v[72:73], v[72:73], v[102:103]
	v_pk_mul_f32 v[82:83], v[68:69], v[84:85]
	v_lshl_add_u64 v[70:71], s[46:47], 0, v[70:71]
	v_cvt_pk_bf16_f32 v68, v72, v73
	v_cvt_pk_bf16_f32 v69, v82, v83
	v_lshl_add_u64 v[70:71], v[70:71], 0, v[4:5]
	global_store_dwordx4 v[70:71], v[66:69], off offset:1024
	s_cbranch_execnz .LBB0_559

.LBB0_568:
	s_or_b64 exec, exec, s[22:23]
	v_mov_b32_e32 v3, v0
	s_mov_b64 s[22:23], -1
	v_and_b32_e32 v88, 15, v3
	s_waitcnt vmcnt(5)
	v_bfe_u32 v2, v3, 4, 2
	v_or_b32_e32 v4, s82, v88
	ds_read_b64_tr_b16 v[66:67], v241
	ds_read_b64_tr_b16 v[68:69], v241 offset:1024
	ds_read_b64_tr_b16 v[74:75], v241 offset:32768
	ds_read_b64_tr_b16 v[76:77], v241 offset:33792
	ds_read_b64_tr_b16 v[70:71], v241 offset:2048
	ds_read_b64_tr_b16 v[72:73], v241 offset:3072
	ds_read_b64_tr_b16 v[78:79], v241 offset:34816
	ds_read_b64_tr_b16 v[80:81], v241 offset:35840
	v_lshlrev_b32_e32 v92, 2, v2
	s_and_b64 vcc, exec, s[4:5]
	v_lshlrev_b32_e32 v86, 5, v4
	v_lshlrev_b32_e32 v87, 3, v2
	v_cmp_lt_u32_e64 s[18:19], v92, v88
	v_or_b32_e32 v91, 1, v92
	v_or_b32_e32 v90, 2, v92
	v_or_b32_e32 v89, 3, v92
	s_cbranch_vccz .LBB0_576
	ds_read_b64_tr_b16 v[94:95], v241 offset:8
	ds_read_b64_tr_b16 v[96:97], v241 offset:1032
	ds_read_b64_tr_b16 v[106:107], v241 offset:32776
	ds_read_b64_tr_b16 v[108:109], v241 offset:33800
	ds_read_b64_tr_b16 v[98:99], v241 offset:2056
	ds_read_b64_tr_b16 v[100:101], v241 offset:3080
	s_waitcnt lgkmcnt(4)
	v_mfma_f32_16x16x32_bf16 v[102:105], v[74:77], v[94:97], 0
	ds_read_b64_tr_b16 v[82:83], v241 offset:34824
	ds_read_b64_tr_b16 v[84:85], v241 offset:35848
	v_cmp_gt_u32_e64 s[24:25], v90, v88
	v_mov_b32_e32 v118, s67
	v_mov_b32_e32 v120, s67
	s_waitcnt lgkmcnt(4)
	v_mfma_f32_16x16x32_bf16 v[114:117], v[106:109], v[94:97], 0
	v_cmp_gt_u32_e32 vcc, v92, v88
	v_cmp_lt_u32_e64 s[22:23], v90, v88
	v_lshlrev_b32_e32 v4, 6, v4
	v_mfma_f32_16x16x32_bf16 v[110:113], v[106:109], v[66:69], 0
	v_lshlrev_b32_e32 v122, 16, v94
	v_and_b32_e32 v123, 0xffff0000, v94
	v_and_b32_e32 v3, 3, v3
	s_waitcnt lgkmcnt(2)
	v_mfma_f32_16x16x32_bf16 v[102:105], v[78:81], v[98:101], v[102:105]
	s_waitcnt lgkmcnt(0)
	v_mfma_f32_16x16x32_bf16 v[114:117], v[82:85], v[98:101], v[114:117]
	v_mfma_f32_16x16x32_bf16 v[110:113], v[82:85], v[70:73], v[110:113]
	s_nop 4
	v_cndmask_b32_e64 v104, v104, 0, s[24:25]
	s_nop 0
	v_cndmask_b32_e64 v116, v116, 0, s[24:25]
	v_cmp_lt_u32_e64 s[24:25], v89, v88
	v_cndmask_b32_e32 v93, v114, v120, vcc
	v_cndmask_b32_e32 v118, v102, v118, vcc
	v_cmp_lt_u32_e32 vcc, v91, v88
	s_or_b64 s[22:23], s[24:25], s[22:23]
	s_or_b64 vcc, s[22:23], vcc
	v_cndmask_b32_e64 v93, v93, v114, s[18:19]
	v_cndmask_b32_e64 v114, 0, v115, s[18:19]
	v_cndmask_b32_e64 v115, v118, v102, s[18:19]
	v_cndmask_b32_e32 v102, 0, v111, vcc
	s_or_b64 vcc, vcc, s[18:19]
	v_cndmask_b32_e64 v118, 0, v103, s[18:19]
	v_cndmask_b32_e64 v103, 0, v113, s[24:25]
	v_cndmask_b32_e64 v112, 0, v112, s[22:23]
	v_cndmask_b32_e32 v110, 0, v110, vcc
	v_cmp_gt_u32_e32 vcc, v89, v88
	v_cvt_pk_bf16_f32 v102, v110, v102
	v_cvt_pk_bf16_f32 v103, v112, v103
	v_cndmask_b32_e64 v105, v105, 0, vcc
	v_add3_u32 v110, s72, v86, v87
	v_cndmask_b32_e64 v111, v117, 0, vcc
	ds_write_b64 v110, v[102:103]
	v_cvt_pk_bf16_f32 v103, v104, v105
	v_cvt_pk_bf16_f32 v104, v93, v114
	v_lshlrev_b32_e32 v93, 4, v2
	v_cvt_pk_bf16_f32 v102, v115, v118
	v_cvt_pk_bf16_f32 v105, v116, v111
	v_add3_u32 v4, s71, v4, v93
	ds_write_b128 v4, v[102:105]
	v_lshl_add_u32 v4, v2, 5, 0
	ds_read_b128 v[102:105], v4 offset:22016
	ds_read_b128 v[110:113], v4 offset:22032
	ds_read_b128 v[114:117], v4 offset:22144
	ds_read_b128 v[118:121], v4 offset:22160
	v_cmp_lt_i32_e32 vcc, 0, v3
	s_waitcnt lgkmcnt(3)
	v_pk_mul_f32 v[102:103], v[102:103], v[122:123]
	s_nop 0
	v_cvt_pk_bf16_f32 v94, v102, v103
	v_lshlrev_b32_e32 v102, 16, v98
	v_and_b32_e32 v103, 0xffff0000, v98
	s_waitcnt lgkmcnt(1)
	v_pk_mul_f32 v[102:103], v[114:115], v[102:103]
	s_nop 0
	v_cvt_pk_bf16_f32 v98, v102, v103
	v_lshlrev_b32_e32 v102, 16, v95
	v_and_b32_e32 v103, 0xffff0000, v95
	v_pk_mul_f32 v[102:103], v[104:105], v[102:103]
	s_nop 0
	v_cvt_pk_bf16_f32 v95, v102, v103
	v_lshlrev_b32_e32 v102, 16, v99
	v_and_b32_e32 v103, 0xffff0000, v99
	v_pk_mul_f32 v[102:103], v[116:117], v[102:103]
	s_nop 0
	v_cvt_pk_bf16_f32 v99, v102, v103
	v_lshlrev_b32_e32 v102, 16, v96
	v_and_b32_e32 v103, 0xffff0000, v96
	v_pk_mul_f32 v[102:103], v[110:111], v[102:103]
	s_nop 0
	v_cvt_pk_bf16_f32 v96, v102, v103
	v_lshlrev_b32_e32 v102, 16, v100
	v_and_b32_e32 v103, 0xffff0000, v100
	s_waitcnt lgkmcnt(0)
	v_pk_mul_f32 v[102:103], v[118:119], v[102:103]
	s_nop 0
	v_cvt_pk_bf16_f32 v100, v102, v103
	v_lshlrev_b32_e32 v102, 16, v97
	v_and_b32_e32 v103, 0xffff0000, v97
	v_pk_mul_f32 v[102:103], v[112:113], v[102:103]
	s_nop 0
	v_cvt_pk_bf16_f32 v97, v102, v103
	v_lshlrev_b32_e32 v102, 16, v101
	v_and_b32_e32 v103, 0xffff0000, v101
	v_mfma_f32_16x16x32_bf16 v[94:97], v[106:109], v[94:97], 0
	v_mul_f32_e64 v102, v120, v102
	v_mul_f32_e64 v103, v121, v103
	v_cvt_pk_bf16_f32 v101, v102, v103
	s_nop 1
	v_mfma_f32_16x16x32_bf16 v[82:85], v[82:85], v[98:101], v[94:97]
	s_and_saveexec_b64 s[18:19], vcc
	s_xor_b64 s[18:19], exec, s[18:19]
	s_cbranch_execz .LBB0_573
	v_cmp_ne_u32_e32 vcc, 1, v3
	s_nop 3
	v_mov_b32_e32 v82, v83
	s_and_saveexec_b64 s[22:23], vcc
	s_xor_b64 s[22:23], exec, s[22:23]
	v_cmp_eq_u32_e32 vcc, 2, v3
	s_nop 1
	v_cndmask_b32_e32 v82, v85, v84, vcc
	s_andn2_saveexec_b64 s[22:23], s[22:23]
	s_or_b64 exec, exec, s[22:23]

.LBB0_576:
	s_and_b64 vcc, exec, s[22:23]
	s_cbranch_vccz .LBB0_578
	s_waitcnt lgkmcnt(4)
	v_mfma_f32_16x16x32_bf16 v[82:85], v[66:69], v[74:77], 0
	v_cmp_lt_u32_e64 s[22:23], v88, v90
	v_cmp_lt_u32_e64 s[24:25], v88, v89
	v_cmp_lt_u32_e32 vcc, v88, v92
	s_waitcnt lgkmcnt(0)
	v_mfma_f32_16x16x32_bf16 v[82:85], v[70:73], v[78:81], v[82:85]
	v_mov_b32_e32 v2, s67
	v_cmp_lt_u32_e64 s[18:19], v91, v88
	v_mfma_f32_16x16x32_bf16 v[66:69], v[74:77], v[66:69], 0
	v_mfma_f32_16x16x32_bf16 v[66:69], v[78:81], v[70:73], v[66:69]
	s_nop 3
	v_cndmask_b32_e64 v4, 0, v84, s[22:23]
	v_cmp_lt_u32_e64 s[22:23], v90, v88
	v_cndmask_b32_e64 v70, 0, v85, s[24:25]
	v_cmp_lt_u32_e64 s[24:25], v89, v88
	s_or_b64 s[22:23], s[24:25], s[22:23]
	v_cndmask_b32_e32 v2, v2, v82, vcc
	v_cmp_lt_u32_e32 vcc, v92, v88
	s_or_b64 s[18:19], s[22:23], s[18:19]
	v_cndmask_b32_e64 v76, 0, v68, s[22:23]
	v_cndmask_b32_e64 v3, v83, 0, vcc
	s_or_b64 vcc, s[18:19], vcc
	v_cndmask_b32_e64 v75, 0, v67, s[18:19]
	v_cndmask_b32_e32 v74, 0, v66, vcc
	v_cndmask_b32_e64 v77, 0, v69, s[24:25]
	v_cvt_pk_bf16_f32 v2, v2, v3
	v_cvt_pk_bf16_f32 v3, v4, v70
	v_mov_b32_e32 v4, v5
	v_cvt_pk_bf16_f32 v66, v74, v75
	v_cvt_pk_bf16_f32 v67, v76, v77
	v_mov_b32_e32 v68, v5
	v_mov_b32_e32 v69, v5
	v_cmp_eq_u32_e32 vcc, v92, v88
	v_add_f32_e32 v78, 1.0, v74
	v_mfma_f32_16x16x32_bf16 v[70:73], v[66:69], v[2:5], 0
	v_cndmask_b32_e32 v74, v74, v78, vcc
	v_cmp_eq_u32_e32 vcc, v91, v88
	v_add_f32_e32 v78, 1.0, v75
	v_mfma_f32_16x16x32_bf16 v[66:69], v[2:5], v[66:69], 0
	s_nop 3
	v_cvt_pk_bf16_f32 v2, v70, v71
	v_cvt_pk_bf16_f32 v3, v72, v73
	v_cndmask_b32_e32 v75, v75, v78, vcc
	v_cmp_eq_u32_e32 vcc, v90, v88
	v_add_f32_e32 v78, 1.0, v76
	v_cvt_pk_bf16_f32 v66, v66, v67
	v_cvt_pk_bf16_f32 v67, v68, v69
	v_mov_b32_e32 v68, v5
	v_mov_b32_e32 v69, v5
	v_cndmask_b32_e32 v76, v76, v78, vcc
	v_cmp_eq_u32_e32 vcc, v89, v88
	v_mfma_f32_16x16x32_bf16 v[70:73], v[66:69], v[2:5], 0
	v_add_f32_e32 v78, 1.0, v77
	v_cndmask_b32_e32 v77, v77, v78, vcc
	v_cvt_pk_bf16_f32 v78, v74, v75
	v_mfma_f32_16x16x32_bf16 v[66:69], v[2:5], v[66:69], 0
	v_cvt_pk_bf16_f32 v79, v76, v77
	v_mov_b32_e32 v80, v5
	v_mov_b32_e32 v81, v5
	s_nop 0
	v_cvt_pk_bf16_f32 v70, v70, v71
	v_cvt_pk_bf16_f32 v71, v72, v73
	s_nop 1
	v_cvt_pk_bf16_f32 v66, v66, v67
	v_cvt_pk_bf16_f32 v67, v68, v69
	v_mov_b32_e32 v68, v5
	v_mov_b32_e32 v69, v5
	v_mov_b32_e32 v72, v5
	v_mov_b32_e32 v73, v5
	v_mfma_f32_16x16x32_bf16 v[74:77], v[2:5], v[78:81], v[74:77]
	s_nop 0
	v_mfma_f32_16x16x32_bf16 v[66:69], v[66:69], v[70:73], 0
	s_nop 5
	v_cvt_pk_bf16_f32 v2, v74, v75
	v_cvt_pk_bf16_f32 v3, v76, v77
	s_nop 1
	v_mfma_f32_16x16x32_bf16 v[70:73], v[70:73], v[2:5], v[74:77]
	v_cvt_pk_bf16_f32 v2, v66, v67
	v_cvt_pk_bf16_f32 v3, v68, v69
	v_mov_b32_e32 v68, v5
	v_mov_b32_e32 v69, v5
	s_nop 3
	v_cvt_pk_bf16_f32 v66, v70, v71
	v_cvt_pk_bf16_f32 v67, v72, v73
	s_nop 1
	v_mfma_f32_16x16x32_bf16 v[66:69], v[2:5], v[66:69], v[70:73]
	v_add3_u32 v4, s33, v86, v87
	s_nop 6
	v_cvt_pk_bf16_f32 v2, v66, v67
	v_cvt_pk_bf16_f32 v3, v68, v69
	ds_write_b64 v4, v[2:3]

.LBB0_606:
	s_andn2_b64 vcc, exec, s[18:19]
	s_cbranch_vccnz .LBB0_540
	v_mov_b32_e32 v4, v0
	v_mov_b32_e32 v76, v5
	v_lshrrev_b32_e32 v38, 4, v4
	v_bfe_u32 v135, v4, 4, 2
	v_and_b32_e32 v134, 15, v4
	ds_read_b64_tr_b16 v[50:51], v253
	ds_read_b64_tr_b16 v[52:53], v253 offset:1024
	ds_read_b64_tr_b16 v[54:55], v253 offset:2048
	ds_read_b64_tr_b16 v[56:57], v253 offset:3072
	v_lshlrev_b32_e32 v39, 5, v134
	v_lshlrev_b32_e32 v138, 3, v135
	v_or_b32_e32 v40, v138, v39
	ds_read_b64_tr_b16 v[58:59], v253 offset:8
	ds_read_b64_tr_b16 v[60:61], v253 offset:1032
	ds_read_b64_tr_b16 v[62:63], v253 offset:2056
	ds_read_b64_tr_b16 v[64:65], v253 offset:3080
	v_add_u32_e32 v2, s72, v40
	v_add_u32_e32 v41, s33, v40
	v_lshrrev_b32_e32 v4, 2, v4
	ds_read_b64 v[2:3], v2
	ds_read_b64 v[66:67], v41
	v_or_b32_e32 v41, s84, v134
	v_xor_b32_e32 v4, v38, v4
	v_lshl_add_u32 v40, v40, 1, s71
	v_lshl_add_u32 v139, v41, 7, s31
	v_bitop3_b32 v41, v38, v134, 3 bitop3:0x6c
	v_lshlrev_b32_e32 v4, 3, v4
	v_lshl_add_u32 v41, v41, 3, v139
	ds_read_b128 v[70:73], v40
	ds_read_b64 v[74:75], v41
	v_and_b32_e32 v40, 24, v4
	v_or_b32_e32 v4, v40, v39
	v_lshl_add_u32 v4, v4, 1, 0
	v_add_u32_e32 v38, 0x1a540, v4
	v_add_u32_e32 v39, 0x1a940, v4
	ds_read_b128 v[78:81], v38
	ds_read_b128 v[82:85], v39
	v_add_u32_e32 v38, 0x1ad40, v4
	v_add_u32_e32 v4, 0x1b140, v4
	ds_read_b128 v[86:89], v38
	ds_read_b128 v[90:93], v4
	v_or_b32_e32 v4, 16, v134
	v_lshlrev_b32_e32 v212, 4, v135
	s_waitcnt vmcnt(4)
	v_add_u32_e32 v213, 0, v212
	ds_read_b128 v[94:97], v213 offset:20992
	ds_read_b128 v[98:101], v213 offset:21056
	ds_read_b128 v[102:105], v213 offset:21120
	ds_read_b128 v[106:109], v213 offset:21184
	ds_read_b64_tr_b16 v[110:111], v253 offset:4096
	ds_read_b64_tr_b16 v[112:113], v253 offset:5120
	ds_read_b64_tr_b16 v[46:47], v253 offset:6144
	ds_read_b64_tr_b16 v[48:49], v253 offset:7168
	ds_read_b64_tr_b16 v[114:115], v253 offset:4104
	ds_read_b64_tr_b16 v[116:117], v253 offset:5128
	ds_read_b64_tr_b16 v[42:43], v253 offset:6152
	ds_read_b64_tr_b16 v[44:45], v253 offset:7176
	v_lshl_or_b32 v38, v4, 5, v138
	v_lshlrev_b32_e32 v4, 6, v4
	v_add3_u32 v41, s71, v4, v212
	v_bitop3_b32 v4, v135, v134, 4 bitop3:0x36
	v_lshl_add_u32 v68, v4, 3, v139
	v_mov_b32_e32 v4, v5
	v_mov_b32_e32 v77, v5
	v_cvt_pk_bf16_f32 v120, v22, v23
	v_cvt_pk_bf16_f32 v121, v24, v25
	s_waitcnt lgkmcnt(14)
	v_mfma_f32_16x16x32_bf16 v[124:127], v[2:5], v[74:77], 0
	v_cvt_pk_bf16_f32 v122, v26, v27
	v_cvt_pk_bf16_f32 v123, v28, v29
	v_add_u32_e32 v39, s72, v38
	v_add_u32_e32 v38, s33, v38
	v_mfma_f32_16x16x32_bf16 v[50:53], v[50:53], v[120:123], v[124:127]
	v_cvt_pk_bf16_f32 v128, v30, v31
	v_cvt_pk_bf16_f32 v129, v32, v33
	v_cvt_pk_bf16_f32 v130, v34, v35
	v_cvt_pk_bf16_f32 v131, v36, v37
	ds_read_b64 v[118:119], v39
	ds_read_b64 v[38:39], v38
	v_mfma_f32_16x16x32_bf16 v[50:53], v[54:57], v[128:131], v[50:53]
	ds_read_b128 v[54:57], v41
	ds_read_b64 v[76:77], v68
	v_mov_b32_e32 v68, v5
	v_mov_b32_e32 v69, v5
	v_mfma_f32_16x16x32_bf16 v[58:61], v[58:61], v[120:123], 0
	s_nop 2
	v_cvt_pk_bf16_f32 v2, v50, v51
	v_cvt_pk_bf16_f32 v3, v52, v53
	v_mov_b32_e32 v120, v5
	v_mfma_f32_16x16x32_bf16 v[58:61], v[62:65], v[128:131], v[58:61]
	v_mov_b32_e32 v121, v5
	v_lshlrev_b32_e32 v41, 6, v134
	v_lshlrev_b32_e32 v40, 1, v40
	v_mfma_f32_16x16x32_bf16 v[50:53], v[66:69], v[2:5], 0
	v_add3_u32 v214, 0, v41, v40
	v_add_u32_e32 v2, 0x1b540, v214
	v_add_u32_e32 v3, 0x1b940, v214
	ds_read_b128 v[62:65], v2
	ds_read_b128 v[66:69], v3
	s_nop 2
	v_cvt_pk_bf16_f32 v50, v50, v51
	v_cvt_pk_bf16_f32 v51, v52, v53
	v_mov_b32_e32 v52, v74
	v_mov_b32_e32 v53, v75
	v_add_u32_e32 v2, 0x1bd40, v214
	v_add_u32_e32 v3, 0x1c140, v214
	v_mfma_f32_16x16x32_bf16 v[22:25], v[78:81], v[50:53], v[22:25]
	v_lshlrev_b32_e32 v215, 1, v134
	v_lshlrev_b32_e32 v216, 9, v135
	v_mov_b32_e32 v78, v5
	v_mfma_f32_16x16x32_bf16 v[26:29], v[82:85], v[50:53], v[26:29]
	v_mov_b32_e32 v79, v5
	s_nop 1
	s_waitcnt lgkmcnt(14)
	v_pk_mul_f32 v[24:25], v[96:97], v[24:25]
	v_pk_mul_f32 v[22:23], v[94:95], v[22:23]
	v_mfma_f32_16x16x32_bf16 v[30:33], v[86:89], v[50:53], v[30:33]
	ds_read_b128 v[80:83], v2
	ds_read_b128 v[84:87], v3
	ds_read_b128 v[122:125], v213 offset:21248
	ds_read_b128 v[126:129], v213 offset:21312
	v_add3_u32 v3, s85, v215, v216
	v_pk_mul_f32 v[28:29], v[100:101], v[28:29]
	v_mfma_f32_16x16x32_bf16 v[34:37], v[90:93], v[50:53], v[34:37]
	s_nop 0
	v_mul_f32_e64 v32, v104, v32
	v_mul_f32_e64 v33, v105, v33
	v_pk_mul_f32 v[30:31], v[102:103], v[30:31]
	ds_read_b128 v[88:91], v213 offset:21376
	ds_read_b128 v[130:133], v213 offset:21440
	v_mfma_f32_16x16x32_bf16 v[50:53], v[70:73], v[50:53], v[58:61]
	v_mul_f32_e64 v26, v98, v26
	v_mul_f32_e64 v27, v99, v27
	v_cvt_pk_bf16_f32 v98, v22, v23
	s_waitcnt lgkmcnt(8)
	v_mfma_f32_16x16x32_bf16 v[102:105], v[118:121], v[76:79], 0
	v_cvt_pk_bf16_f32 v99, v24, v25
	s_nop 1
	v_cvt_pk_bf16_f32 v2, v50, s0
	ds_write_b16 v3, v2
	v_cvt_pk_bf16_f32 v2, v51, s0
	ds_write_b16 v3, v2 offset:128
	v_cvt_pk_bf16_f32 v2, v52, s0
	ds_write_b16 v3, v2 offset:256
	v_cvt_pk_bf16_f32 v2, v53, s0
	v_cvt_pk_bf16_f32 v100, v26, v27
	v_cvt_pk_bf16_f32 v101, v28, v29
	ds_write_b16 v3, v2 offset:384
	v_or_b32_e32 v2, 32, v134
	v_mfma_f32_16x16x32_bf16 v[102:105], v[110:113], v[98:101], v[102:105]
	v_pk_mul_f32 v[36:37], v[108:109], v[36:37]
	v_pk_mul_f32 v[34:35], v[106:107], v[34:35]
	v_cvt_pk_bf16_f32 v106, v30, v31
	v_cvt_pk_bf16_f32 v107, v32, v33
	v_cvt_pk_bf16_f32 v108, v34, v35
	v_cvt_pk_bf16_f32 v109, v36, v37
	ds_read_b64_tr_b16 v[50:51], v253 offset:8192
	ds_read_b64_tr_b16 v[52:53], v253 offset:9216
	ds_read_b64_tr_b16 v[58:59], v253 offset:10240
	ds_read_b64_tr_b16 v[60:61], v253 offset:11264
	v_mfma_f32_16x16x32_bf16 v[46:49], v[46:49], v[106:109], v[102:105]
	v_mov_b32_e32 v40, v5
	v_mov_b32_e32 v41, v5
	ds_read_b64_tr_b16 v[70:71], v253 offset:8200
	ds_read_b64_tr_b16 v[72:73], v253 offset:9224
	ds_read_b64_tr_b16 v[92:93], v253 offset:10248
	ds_read_b64_tr_b16 v[94:95], v253 offset:11272
	v_lshl_or_b32 v3, v2, 5, v138
	v_lshlrev_b32_e32 v2, 6, v2
	v_add_u32_e32 v4, s72, v3
	v_add_u32_e32 v3, s33, v3
	v_add3_u32 v78, s71, v2, v212
	v_bitop3_b32 v2, v135, v134, 8 bitop3:0x36
	ds_read_b64 v[74:75], v4
	ds_read_b64 v[96:97], v3
	v_mfma_f32_16x16x32_bf16 v[98:101], v[114:117], v[98:101], 0
	v_lshl_add_u32 v79, v2, 3, v139
	v_cvt_pk_bf16_f32 v2, v46, v47
	v_cvt_pk_bf16_f32 v3, v48, v49
	v_mov_b32_e32 v4, v5
	v_mfma_f32_16x16x32_bf16 v[42:45], v[42:45], v[106:109], v[98:101]
	s_nop 0
	v_mfma_f32_16x16x32_bf16 v[38:41], v[38:41], v[2:5], 0
	v_add_u32_e32 v2, 0x1c540, v214
	v_add_u32_e32 v3, 0x1c940, v214
	v_mov_b32_e32 v98, v5
	v_mov_b32_e32 v99, v5
	s_nop 3
	v_cvt_pk_bf16_f32 v38, v38, v39
	v_cvt_pk_bf16_f32 v39, v40, v41
	v_mov_b32_e32 v40, v76
	v_mov_b32_e32 v41, v77
	v_mov_b32_e32 v76, v5
	v_mov_b32_e32 v77, v5
	s_waitcnt lgkmcnt(14)
	v_mfma_f32_16x16x32_bf16 v[22:25], v[62:65], v[38:41], v[22:25]
	ds_read_b128 v[46:49], v78
	ds_read_b64 v[62:63], v79
	v_mov_b32_e32 v64, v5
	v_mov_b32_e32 v65, v5
	v_mfma_f32_16x16x32_bf16 v[26:29], v[66:69], v[38:41], v[26:29]
	ds_read_b128 v[66:69], v2
	ds_read_b128 v[100:103], v3
	v_add_u32_e32 v2, 0x1cd40, v214
	v_add_u32_e32 v3, 0x1d140, v214
	v_mfma_f32_16x16x32_bf16 v[30:33], v[80:83], v[38:41], v[30:33]
	ds_read_b128 v[78:81], v2
	ds_read_b128 v[104:107], v3
	ds_read_b128 v[108:111], v213 offset:21504
	ds_read_b128 v[112:115], v213 offset:21568
	v_add3_u32 v3, s86, v215, v216
	v_pk_mul_f32 v[24:25], v[124:125], v[24:25]
	v_mfma_f32_16x16x32_bf16 v[34:37], v[84:87], v[38:41], v[34:37]
	ds_read_b128 v[82:85], v213 offset:21632
	ds_read_b128 v[116:119], v213 offset:21696
	v_pk_mul_f32 v[22:23], v[122:123], v[22:23]
	v_mfma_f32_16x16x32_bf16 v[38:41], v[54:57], v[38:41], v[42:45]
	v_mul_f32_e64 v28, v128, v28
	v_mul_f32_e64 v29, v129, v29
	v_pk_mul_f32 v[26:27], v[126:127], v[26:27]
	v_cvt_pk_bf16_f32 v122, v22, v23
	s_waitcnt lgkmcnt(8)
	v_mfma_f32_16x16x32_bf16 v[74:77], v[74:77], v[62:65], 0
	v_cvt_pk_bf16_f32 v123, v24, v25
	s_nop 0
	v_cvt_pk_bf16_f32 v2, v38, s0
	ds_write_b16 v3, v2
	v_cvt_pk_bf16_f32 v2, v39, s0
	ds_write_b16 v3, v2 offset:128
	v_cvt_pk_bf16_f32 v2, v40, s0
	v_cvt_pk_bf16_f32 v124, v26, v27
	v_cvt_pk_bf16_f32 v125, v28, v29
	ds_write_b16 v3, v2 offset:256
	v_cvt_pk_bf16_f32 v2, v41, s0
	v_mfma_f32_16x16x32_bf16 v[50:53], v[50:53], v[122:125], v[74:77]
	ds_write_b16 v3, v2 offset:384
	v_or_b32_e32 v2, 48, v134
	v_pk_mul_f32 v[32:33], v[90:91], v[32:33]
	v_pk_mul_f32 v[30:31], v[88:89], v[30:31]
	v_pk_mul_f32 v[36:37], v[132:133], v[36:37]
	v_pk_mul_f32 v[34:35], v[130:131], v[34:35]
	v_cvt_pk_bf16_f32 v126, v30, v31
	v_cvt_pk_bf16_f32 v127, v32, v33
	v_cvt_pk_bf16_f32 v128, v34, v35
	v_cvt_pk_bf16_f32 v129, v36, v37
	s_nop 0
	s_nop 0
	v_mfma_f32_16x16x32_bf16 v[50:53], v[58:61], v[126:129], v[50:53]
	ds_read_b64_tr_b16 v[38:39], v253 offset:12288
	ds_read_b64_tr_b16 v[40:41], v253 offset:13312
	ds_read_b64_tr_b16 v[42:43], v253 offset:14336
	ds_read_b64_tr_b16 v[44:45], v253 offset:15360
	ds_read_b64_tr_b16 v[54:55], v253 offset:12296
	ds_read_b64_tr_b16 v[56:57], v253 offset:13320
	ds_read_b64_tr_b16 v[86:87], v253 offset:14344
	ds_read_b64_tr_b16 v[88:89], v253 offset:15368
	v_lshl_or_b32 v3, v2, 5, v138
	v_lshlrev_b32_e32 v2, 6, v2
	v_add_u32_e32 v4, s72, v3
	v_add_u32_e32 v3, s33, v3
	v_add3_u32 v64, s71, v2, v212
	v_bitop3_b32 v2, v135, v134, 12 bitop3:0x36
	ds_read_b64 v[90:91], v4
	ds_read_b64 v[120:121], v3
	v_mfma_f32_16x16x32_bf16 v[58:61], v[70:73], v[122:125], 0
	v_lshl_add_u32 v70, v2, 3, v139
	v_cvt_pk_bf16_f32 v2, v50, v51
	v_cvt_pk_bf16_f32 v3, v52, v53
	v_mov_b32_e32 v4, v5
	v_mfma_f32_16x16x32_bf16 v[58:61], v[92:95], v[126:129], v[58:61]
	v_mov_b32_e32 v92, v5
	v_mov_b32_e32 v93, v5
	v_mov_b32_e32 v122, v5
	v_mfma_f32_16x16x32_bf16 v[50:53], v[96:99], v[2:5], 0
	v_add_u32_e32 v2, 0x1d540, v214
	v_mov_b32_e32 v123, v5
	v_add_u32_e32 v3, 0x1d940, v214
	s_nop 4
	v_cvt_pk_bf16_f32 v50, v50, v51
	v_cvt_pk_bf16_f32 v51, v52, v53
	v_mov_b32_e32 v52, v62
	v_mov_b32_e32 v53, v63
	s_nop 0
	s_waitcnt lgkmcnt(14)
	v_mfma_f32_16x16x32_bf16 v[22:25], v[66:69], v[50:53], v[22:25]
	ds_read_b128 v[62:65], v64
	ds_read_b64 v[66:67], v70
	v_mov_b32_e32 v68, v5
	v_mov_b32_e32 v69, v5
	v_mfma_f32_16x16x32_bf16 v[26:29], v[100:103], v[50:53], v[26:29]
	s_nop 1
	s_nop 0
	v_pk_mul_f32 v[24:25], v[110:111], v[24:25]
	v_pk_mul_f32 v[22:23], v[108:109], v[22:23]
	ds_read_b128 v[70:73], v2
	ds_read_b128 v[74:77], v3
	v_mfma_f32_16x16x32_bf16 v[46:49], v[46:49], v[50:53], v[58:61]
	v_mul_f32_e64 v28, v114, v28
	v_mul_f32_e64 v29, v115, v29
	v_pk_mul_f32 v[26:27], v[112:113], v[26:27]
	v_add_u32_e32 v2, 0x1dd40, v214
	s_waitcnt lgkmcnt(2)
	v_mfma_f32_16x16x32_bf16 v[58:61], v[90:93], v[66:69], 0
	v_add_u32_e32 v3, 0x1e140, v214
	v_mfma_f32_16x16x32_bf16 v[30:33], v[78:81], v[50:53], v[30:33]
	ds_read_b128 v[78:81], v2
	ds_read_b128 v[94:97], v3
	ds_read_b128 v[98:101], v213 offset:21760
	ds_read_b128 v[124:127], v213 offset:21824
	v_cvt_pk_bf16_f32 v2, v46, s0
	v_add3_u32 v46, s87, v215, v216
	v_mfma_f32_16x16x32_bf16 v[34:37], v[104:107], v[50:53], v[34:37]
	v_cvt_pk_bf16_f32 v50, v22, v23
	v_cvt_pk_bf16_f32 v51, v24, v25
	v_cvt_pk_bf16_f32 v52, v26, v27
	v_cvt_pk_bf16_f32 v53, v28, v29
	v_pk_mul_f32 v[32:33], v[84:85], v[32:33]
	v_pk_mul_f32 v[30:31], v[82:83], v[30:31]
	v_mfma_f32_16x16x32_bf16 v[38:41], v[38:41], v[50:53], v[58:61]
	s_nop 0
	v_mul_f32_e64 v36, v118, v36
	v_mul_f32_e64 v37, v119, v37
	v_pk_mul_f32 v[34:35], v[116:117], v[34:35]
	v_cvt_pk_bf16_f32 v82, v30, v31
	v_cvt_pk_bf16_f32 v83, v32, v33
	v_cvt_pk_bf16_f32 v84, v34, v35
	v_cvt_pk_bf16_f32 v85, v36, v37
	ds_read_b128 v[102:105], v213 offset:21888
	ds_read_b128 v[128:131], v213 offset:21952
	v_mfma_f32_16x16x32_bf16 v[38:41], v[42:45], v[82:85], v[38:41]
	ds_write_b16 v46, v2
	v_cvt_pk_bf16_f32 v2, v47, s0
	v_mfma_f32_16x16x32_bf16 v[42:45], v[54:57], v[50:53], 0
	ds_write_b16 v46, v2 offset:128
	s_nop 3
	v_cvt_pk_bf16_f32 v2, v38, v39
	v_cvt_pk_bf16_f32 v3, v40, v41
	v_mfma_f32_16x16x32_bf16 v[42:45], v[86:89], v[82:85], v[42:45]
	s_nop 0
	v_mfma_f32_16x16x32_bf16 v[38:41], v[120:123], v[2:5], 0
	v_cvt_pk_bf16_f32 v2, v48, s0
	ds_write_b16 v46, v2 offset:256
	v_cvt_pk_bf16_f32 v2, v49, s0
	ds_write_b16 v46, v2 offset:384
	v_add3_u32 v3, s88, v215, v216
	s_nop 2
	v_cvt_pk_bf16_f32 v38, v38, v39
	v_cvt_pk_bf16_f32 v39, v40, v41
	v_mov_b32_e32 v40, v66
	v_mov_b32_e32 v41, v67
	s_nop 0
	s_waitcnt lgkmcnt(11)
	v_mfma_f32_16x16x32_bf16 v[22:25], v[70:73], v[38:41], v[22:25]
	s_waitcnt lgkmcnt(10)
	v_mfma_f32_16x16x32_bf16 v[26:29], v[74:77], v[38:41], v[26:29]
	s_waitcnt lgkmcnt(9)
	v_mfma_f32_16x16x32_bf16 v[30:33], v[78:81], v[38:41], v[30:33]
	s_nop 2
	s_waitcnt lgkmcnt(7)
	v_pk_mul_f32 v[24:25], v[100:101], v[24:25]
	v_pk_mul_f32 v[22:23], v[98:99], v[22:23]
	s_waitcnt lgkmcnt(6)
	v_pk_mul_f32 v[28:29], v[126:127], v[28:29]
	v_mfma_f32_16x16x32_bf16 v[34:37], v[94:97], v[38:41], v[34:37]
	v_mul_f32_e64 v26, v124, v26
	v_mul_f32_e64 v27, v125, v27
	s_waitcnt lgkmcnt(5)
	v_pk_mul_f32 v[32:33], v[104:105], v[32:33]
	v_pk_mul_f32 v[30:31], v[102:103], v[30:31]
	v_mfma_f32_16x16x32_bf16 v[38:41], v[62:65], v[38:41], v[42:45]
	s_nop 0
	s_waitcnt lgkmcnt(4)
	v_pk_mul_f32 v[36:37], v[130:131], v[36:37]
	s_nop 4
	v_cvt_pk_bf16_f32 v2, v38, s0
	ds_write_b16 v3, v2
	v_cvt_pk_bf16_f32 v2, v39, s0
	ds_write_b16 v3, v2 offset:128
	v_cvt_pk_bf16_f32 v2, v40, s0
	v_pk_mul_f32 v[34:35], v[128:129], v[34:35]
	ds_write_b16 v3, v2 offset:256
	v_cvt_pk_bf16_f32 v2, v41, s0
	ds_write_b16 v3, v2 offset:384
	s_branch .LBB0_540
